# plus GEMM k-loop: two late B-fragment LDS reads hoisted one MFMA group earlier into free VGPRs (counted lgkmcnt)
# speedup vs baseline: 1.0925x; 1.0068x over previous
.LBB0_639:
	s_add_i32 s41, s28, 1
	s_cmp_lt_u32 s41, s14
	s_cselect_b32 s29, s41, s28
	s_and_b32 s46, s24, 0x10000
	s_lshl_b32 s34, s29, 6
	s_xor_b32 s50, s46, 0x10000
	s_lshl_b64 s[42:43], s[34:35], 1
	s_add_u32 s48, s2, s42
	s_addc_u32 s49, s3, s43
	v_bitop3_b32 v226, s24, v176, v212 bitop3:0xce
	s_add_u32 s42, s4, s42
	s_waitcnt lgkmcnt(0)
	v_mfma_f32_16x16x32_bf16 v[126:129], v[142:145], v[150:153], v[126:129]
	s_addc_u32 s43, s5, s43
	v_lshl_add_u64 v[186:187], v[154:155], 1, s[48:49]
	v_mov_b32_e32 v161, v1
	v_mfma_f32_16x16x32_bf16 v[122:125], v[138:141], v[150:153], v[122:125]
	v_lshl_add_u64 v[186:187], v[186:187], 0, v[0:1]
	v_lshl_add_u64 v[200:201], v[156:157], 1, s[42:43]
	v_add_u32_e32 v185, s46, v181
	v_mfma_f32_16x16x32_bf16 v[118:121], v[134:137], v[150:153], v[118:121]
	s_add_i32 s28, s28, 2
	s_min_i32 s28, s28, s15
	s_lshl_b32 s28, s28, 6
	v_mfma_f32_16x16x32_bf16 v[114:117], v[130:133], v[150:153], v[114:117]
	v_add_u32_e32 v152, v226, v179
	v_lshl_add_u64 v[150:151], v[200:201], 0, v[0:1]
	v_readfirstlane_b32 s29, v152
	v_mfma_f32_16x16x32_bf16 v[110:113], v[142:145], v[146:149], v[110:113]
	v_add_u32_e32 v152, 0x8000, v152
	s_mov_b32 m0, s29
	v_readfirstlane_b32 s29, v152
	v_mfma_f32_16x16x32_bf16 v[106:109], v[138:141], v[146:149], v[106:109]
	global_load_lds_dwordx4 v[186:187], off
	s_mov_b32 m0, s29
	v_mfma_f32_16x16x32_bf16 v[102:105], v[134:137], v[146:149], v[102:105]
	global_load_lds_dwordx4 v[150:151], off
	v_add_u32_e32 v186, v185, v183
	v_mfma_f32_16x16x32_bf16 v[98:101], v[130:133], v[146:149], v[98:101]
	v_lshl_add_u64 v[146:147], v[158:159], 1, s[48:49]
	v_lshl_add_u64 v[148:149], v[164:165], 1, s[42:43]
	v_lshl_add_u64 v[146:147], v[146:147], 0, v[160:161]
	v_lshl_add_u64 v[148:149], v[148:149], 0, v[160:161]
	v_add_u32_e32 v161, v226, v180
	ds_read_b128 v[150:153], v186 offset:6144
	ds_read_b128 v[200:203], v186 offset:4096
	v_readfirstlane_b32 s29, v161
	s_mov_b32 m0, s29
	s_waitcnt lgkmcnt(0)
	v_mfma_f32_16x16x32_bf16 v[94:97], v[142:145], v[200:203], v[94:97]
	global_load_lds_dwordx4 v[146:147], off
	v_add_u32_e32 v146, 0x8000, v161
	v_mfma_f32_16x16x32_bf16 v[90:93], v[138:141], v[200:203], v[90:93]
	v_readfirstlane_b32 s29, v146
	s_mov_b32 m0, s29
	v_bitop3_b32 v146, s24, v182, v212 bitop3:0xce
	global_load_lds_dwordx4 v[148:149], off
	v_mfma_f32_16x16x32_bf16 v[86:89], v[134:137], v[200:203], v[86:89]
	v_add_u32_e32 v233, v146, v183
	v_add3_u32 v187, s46, v177, v176
	v_add3_u32 v231, s46, v178, v176
	v_mfma_f32_16x16x32_bf16 v[82:85], v[130:133], v[200:203], v[82:85]
	ds_read_b128 v[146:149], v186 offset:10240
	ds_read_b128 v[200:203], v186 offset:8192
	v_or_b32_e32 v161, s46, v182
	s_ashr_i32 s29, s28, 31
	v_mfma_f32_16x16x32_bf16 v[78:81], v[142:145], v[150:153], v[78:81]
	v_add_u32_e32 v230, 0x8000, v187
	v_add_u32_e32 v232, 0x8000, v231
	v_add3_u32 v234, s50, v181, v183
	v_mfma_f32_16x16x32_bf16 v[74:77], v[138:141], v[150:153], v[74:77]
	v_mfma_f32_16x16x32_bf16 v[70:73], v[134:137], v[150:153], v[70:73]
	v_mfma_f32_16x16x32_bf16 v[66:69], v[130:133], v[150:153], v[66:69]
	s_waitcnt lgkmcnt(0)
	ds_read_b128 v[236:239], v186 offset:12288
	v_mfma_f32_16x16x32_bf16 v[46:49], v[142:145], v[146:149], v[46:49]
	v_add_u32_e32 v161, v161, v184
	v_mfma_f32_16x16x32_bf16 v[42:45], v[138:141], v[146:149], v[42:45]
	v_mfma_f32_16x16x32_bf16 v[34:37], v[134:137], v[146:149], v[34:37]
	v_mfma_f32_16x16x32_bf16 v[30:33], v[130:133], v[146:149], v[30:33]
	ds_read_b128 v[240:243], v186 offset:14336
	s_waitcnt lgkmcnt(1)
	v_mfma_f32_16x16x32_bf16 v[38:41], v[142:145], v[236:239], v[38:41]
	v_mfma_f32_16x16x32_bf16 v[26:29], v[138:141], v[236:239], v[26:29]
	v_mfma_f32_16x16x32_bf16 v[22:25], v[134:137], v[236:239], v[22:25]
	v_mfma_f32_16x16x32_bf16 v[18:21], v[130:133], v[236:239], v[18:21]
	v_mfma_f32_16x16x32_bf16 v[62:65], v[142:145], v[200:203], v[62:65]
	v_mfma_f32_16x16x32_bf16 v[58:61], v[138:141], v[200:203], v[58:61]
	v_mfma_f32_16x16x32_bf16 v[54:57], v[134:137], v[200:203], v[54:57]
	v_mfma_f32_16x16x32_bf16 v[50:53], v[130:133], v[200:203], v[50:53]
	s_waitcnt lgkmcnt(0)
	v_mfma_f32_16x16x32_bf16 v[14:17], v[142:145], v[240:243], v[14:17]
	v_mfma_f32_16x16x32_bf16 v[10:13], v[138:141], v[240:243], v[10:13]
	ds_read_b128 v[138:141], v161 offset:32768
	ds_read_b128 v[142:145], v161 offset:34816
	ds_read_b128 v[150:153], v161 offset:36864
	ds_read_b128 v[200:203], v161 offset:38912
	v_add_u32_e32 v161, v185, v184
	v_mfma_f32_16x16x32_bf16 v[6:9], v[134:137], v[240:243], v[6:9]
	ds_read_b128 v[134:137], v161 offset:2048
	ds_read_b128 v[226:229], v161
	v_mfma_f32_16x16x32_bf16 v[2:5], v[130:133], v[240:243], v[2:5]
	ds_read_b128 v[130:133], v161 offset:4096
	s_waitcnt lgkmcnt(0)
	v_mfma_f32_16x16x32_bf16 v[110:113], v[138:141], v[134:137], v[110:113]
	v_mfma_f32_16x16x32_bf16 v[94:97], v[138:141], v[130:133], v[94:97]
	v_mfma_f32_16x16x32_bf16 v[90:93], v[142:145], v[130:133], v[90:93]
	v_mfma_f32_16x16x32_bf16 v[86:89], v[150:153], v[130:133], v[86:89]
	v_mfma_f32_16x16x32_bf16 v[82:85], v[200:203], v[130:133], v[82:85]
	ds_read_b128 v[130:133], v161 offset:6144
	v_mfma_f32_16x16x32_bf16 v[106:109], v[142:145], v[134:137], v[106:109]
	v_mfma_f32_16x16x32_bf16 v[102:105], v[150:153], v[134:137], v[102:105]
	v_mfma_f32_16x16x32_bf16 v[98:101], v[200:203], v[134:137], v[98:101]
	ds_read_b128 v[134:137], v161 offset:10240
	ds_read_b128 v[146:149], v161 offset:8192
	v_mfma_f32_16x16x32_bf16 v[126:129], v[138:141], v[226:229], v[126:129]
	v_mfma_f32_16x16x32_bf16 v[122:125], v[142:145], v[226:229], v[122:125]
	v_mfma_f32_16x16x32_bf16 v[118:121], v[150:153], v[226:229], v[118:121]
	v_mfma_f32_16x16x32_bf16 v[114:117], v[200:203], v[226:229], v[114:117]
	s_waitcnt lgkmcnt(0)
	v_mfma_f32_16x16x32_bf16 v[78:81], v[138:141], v[130:133], v[78:81]
	v_mfma_f32_16x16x32_bf16 v[74:77], v[142:145], v[130:133], v[74:77]
	v_mfma_f32_16x16x32_bf16 v[70:73], v[150:153], v[130:133], v[70:73]
	v_mfma_f32_16x16x32_bf16 v[66:69], v[200:203], v[130:133], v[66:69]
	ds_read_b128 v[226:229], v161 offset:14336
	ds_read_b128 v[130:133], v161 offset:12288
	s_lshl_b64 s[28:29], s[28:29], 1
	v_readfirstlane_b32 s34, v187
	v_mfma_f32_16x16x32_bf16 v[46:49], v[138:141], v[134:137], v[46:49]
	s_mov_b32 m0, s34
	v_readfirstlane_b32 s34, v230
	s_waitcnt vmcnt(0)
	v_mfma_f32_16x16x32_bf16 v[42:45], v[142:145], v[134:137], v[42:45]
	s_waitcnt vmcnt(0) lgkmcnt(0)
	s_barrier
	v_mfma_f32_16x16x32_bf16 v[34:37], v[150:153], v[134:137], v[34:37]
	v_mfma_f32_16x16x32_bf16 v[30:33], v[200:203], v[134:137], v[30:33]
	v_lshl_add_u64 v[134:135], v[166:167], 0, s[28:29]
	v_lshl_add_u64 v[136:137], v[168:169], 0, s[28:29]
	global_load_lds_dwordx4 v[134:135], off
	v_mfma_f32_16x16x32_bf16 v[38:41], v[138:141], v[130:133], v[38:41]
	s_mov_b32 m0, s34
	s_nop 0
	global_load_lds_dwordx4 v[136:137], off
	v_mfma_f32_16x16x32_bf16 v[26:29], v[142:145], v[130:133], v[26:29]
	v_mfma_f32_16x16x32_bf16 v[22:25], v[150:153], v[130:133], v[22:25]
	v_mfma_f32_16x16x32_bf16 v[18:21], v[200:203], v[130:133], v[18:21]
	v_lshl_add_u64 v[130:131], v[170:171], 0, s[28:29]
	v_lshl_add_u64 v[132:133], v[172:173], 0, s[28:29]
	v_readfirstlane_b32 s28, v231
	s_mov_b32 m0, s28
	v_readfirstlane_b32 s28, v232
	global_load_lds_dwordx4 v[130:131], off
	s_mov_b32 m0, s28
	v_mfma_f32_16x16x32_bf16 v[62:65], v[138:141], v[146:149], v[62:65]
	global_load_lds_dwordx4 v[132:133], off
	v_mfma_f32_16x16x32_bf16 v[58:61], v[142:145], v[146:149], v[58:61]
	v_mfma_f32_16x16x32_bf16 v[54:57], v[150:153], v[146:149], v[54:57]
	v_mfma_f32_16x16x32_bf16 v[50:53], v[200:203], v[146:149], v[50:53]
	v_mfma_f32_16x16x32_bf16 v[14:17], v[138:141], v[226:229], v[14:17]
	v_mfma_f32_16x16x32_bf16 v[10:13], v[142:145], v[226:229], v[10:13]
	ds_read_b128 v[142:145], v233 offset:32768
	ds_read_b128 v[138:141], v233 offset:34816
	v_mfma_f32_16x16x32_bf16 v[6:9], v[150:153], v[226:229], v[6:9]
	ds_read_b128 v[134:137], v233 offset:36864
	ds_read_b128 v[130:133], v233 offset:38912
	ds_read_b128 v[146:149], v234 offset:2048
	ds_read_b128 v[150:153], v234
	v_mfma_f32_16x16x32_bf16 v[2:5], v[200:203], v[226:229], v[2:5]
	s_add_i32 s24, s24, 0x10000
	s_cmp_eq_u32 s14, s41
	s_mov_b32 s28, s41
	s_cbranch_scc0 .LBB0_639
